# prologue weight-transpose: the 8 per-row gain loads issued together behind one counted wait instead of 8 serialized vmcnt(0) round trips
# speedup vs baseline: 1.0188x; 1.0188x over previous
.LBB0_64:
	v_lshrrev_b32_e32 v67, 3, v194
	v_lshl_or_b32 v28, s36, 6, v67
	v_lshlrev_b32_e32 v0, 2, v194
	v_ashrrev_i32_e32 v29, 31, v28
	v_and_b32_e32 v2, 28, v0
	v_mul_lo_u32 v3, s54, v29
	v_mul_lo_u32 v4, s55, v28
	v_mad_u64_u32 v[0:1], s[4:5], s54, v28, 0
	v_add3_u32 v1, v1, v3, v4
	s_ashr_i32 s59, s58, 31
	v_lshl_add_u64 v[0:1], v[0:1], 2, s[6:7]
	v_mov_b32_e32 v65, 0
	v_lshl_add_u64 v[0:1], s[58:59], 2, v[0:1]
	v_lshlrev_b32_e32 v64, 2, v2
	v_lshl_add_u64 v[0:1], v[0:1], 0, v[64:65]
	global_load_dwordx4 v[0:3], v[0:1], off nt
	s_cmp_lg_u64 s[56:57], 0
	s_cselect_b64 s[60:61], -1, 0
	s_cmp_eq_u64 s[56:57], 0
	v_lshl_add_u64 v[30:31], v[28:29], 2, s[56:57]
	s_cbranch_scc1 .Ltrg0_noload
	global_load_dword v206, v[30:31], off
	global_load_dword v207, v[30:31], off offset:32
	global_load_dword v208, v[30:31], off offset:64
	global_load_dword v209, v[30:31], off offset:96
	global_load_dword v210, v[30:31], off offset:128
	global_load_dword v211, v[30:31], off offset:160
	global_load_dword v212, v[30:31], off offset:192
	global_load_dword v213, v[30:31], off offset:224
.Ltrg0_noload:
	v_mov_b32_e32 v68, v66
	s_cbranch_scc1 .LBB0_66
.LBB0_66:
	v_or_b32_e32 v4, 8, v28
	v_mul_lo_u32 v29, s54, v29
	v_mul_lo_u32 v6, s55, v4
	v_mad_u64_u32 v[4:5], s[4:5], s54, v4, 0
	v_add3_u32 v5, v5, v29, v6
	v_lshl_add_u64 v[4:5], v[4:5], 2, s[6:7]
	v_lshl_add_u64 v[4:5], s[58:59], 2, v[4:5]
	v_lshl_add_u64 v[4:5], v[4:5], 0, v[64:65]
	global_load_dwordx4 v[4:7], v[4:5], off nt
	v_cndmask_b32_e64 v8, 0, 1, s[60:61]
	v_cmp_ne_u32_e64 s[4:5], 1, v8
	s_andn2_b64 vcc, exec, s[60:61]
	v_mov_b32_e32 v70, v66
	s_cbranch_vccnz .LBB0_68
.LBB0_68:
	v_or_b32_e32 v8, 16, v28
	v_mul_lo_u32 v10, s55, v8
	v_mad_u64_u32 v[8:9], s[36:37], s54, v8, 0
	v_add3_u32 v9, v9, v29, v10
	v_lshl_add_u64 v[8:9], v[8:9], 2, s[6:7]
	v_lshl_add_u64 v[8:9], s[58:59], 2, v[8:9]
	v_mov_b32_e32 v65, 0
	v_lshl_add_u64 v[8:9], v[8:9], 0, v[64:65]
	global_load_dwordx4 v[8:11], v[8:9], off nt
	s_and_b64 vcc, exec, s[4:5]
	v_mov_b32_e32 v74, v66
	s_cbranch_vccnz .LBB0_70
.LBB0_70:
	v_or_b32_e32 v12, 24, v28
	v_mul_lo_u32 v14, s55, v12
	v_mad_u64_u32 v[12:13], s[36:37], s54, v12, 0
	v_add3_u32 v13, v13, v29, v14
	v_lshl_add_u64 v[12:13], v[12:13], 2, s[6:7]
	v_lshl_add_u64 v[12:13], s[58:59], 2, v[12:13]
	v_lshl_add_u64 v[12:13], v[12:13], 0, v[64:65]
	global_load_dwordx4 v[12:15], v[12:13], off nt
	s_and_b64 vcc, exec, s[4:5]
	v_mov_b32_e32 v76, v66
	s_cbranch_vccnz .LBB0_72
.LBB0_72:
	v_or_b32_e32 v16, 32, v28
	v_mul_lo_u32 v18, s55, v16
	v_mad_u64_u32 v[16:17], s[36:37], s54, v16, 0
	v_add3_u32 v17, v17, v29, v18
	v_lshl_add_u64 v[16:17], v[16:17], 2, s[6:7]
	v_lshl_add_u64 v[16:17], s[58:59], 2, v[16:17]
	v_mov_b32_e32 v65, 0
	v_lshl_add_u64 v[16:17], v[16:17], 0, v[64:65]
	global_load_dwordx4 v[16:19], v[16:17], off nt
	s_and_b64 vcc, exec, s[4:5]
	v_mov_b32_e32 v78, v66
	s_cbranch_vccnz .LBB0_74
.LBB0_74:
	v_or_b32_e32 v20, 40, v28
	v_mul_lo_u32 v22, s55, v20
	v_mad_u64_u32 v[20:21], s[36:37], s54, v20, 0
	v_add3_u32 v21, v21, v29, v22
	v_lshl_add_u64 v[20:21], v[20:21], 2, s[6:7]
	v_lshl_add_u64 v[20:21], s[58:59], 2, v[20:21]
	v_lshl_add_u64 v[20:21], v[20:21], 0, v[64:65]
	global_load_dwordx4 v[20:23], v[20:21], off nt
	s_and_b64 vcc, exec, s[4:5]
	v_mov_b32_e32 v82, v66
	s_cbranch_vccnz .LBB0_76
.LBB0_76:
	v_or_b32_e32 v24, 48, v28
	v_mul_lo_u32 v26, s55, v24
	v_mad_u64_u32 v[24:25], s[36:37], s54, v24, 0
	v_add3_u32 v25, v25, v29, v26
	v_lshl_add_u64 v[24:25], v[24:25], 2, s[6:7]
	v_lshl_add_u64 v[24:25], s[58:59], 2, v[24:25]
	v_mov_b32_e32 v65, 0
	v_lshl_add_u64 v[24:25], v[24:25], 0, v[64:65]
	global_load_dwordx4 v[24:27], v[24:25], off nt
	s_and_b64 vcc, exec, s[4:5]
	v_mov_b32_e32 v84, v66
	s_cbranch_vccnz .LBB0_78
.LBB0_78:
	v_or_b32_e32 v28, 56, v28
	v_mul_lo_u32 v33, s55, v28
	v_mad_u64_u32 v[34:35], s[36:37], s54, v28, 0
	v_add3_u32 v35, v35, v29, v33
	v_lshl_add_u64 v[28:29], v[34:35], 2, s[6:7]
	v_lshl_add_u64 v[28:29], s[58:59], 2, v[28:29]
	v_lshl_add_u64 v[28:29], v[28:29], 0, v[64:65]
	global_load_dwordx4 v[36:39], v[28:29], off nt
	s_and_b64 vcc, exec, s[4:5]
	s_cbranch_vccnz .LBB0_80
.LBB0_80:
	s_and_b64 vcc, exec, s[4:5]
	s_cbranch_vccnz .Ltrg0_skip
	s_waitcnt vmcnt(7)
	v_mul_f32_e32 v68, v66, v206
	v_mul_f32_e32 v70, v66, v207
	v_mul_f32_e32 v74, v66, v208
	v_mul_f32_e32 v76, v66, v209
	v_mul_f32_e32 v78, v66, v210
	v_mul_f32_e32 v82, v66, v211
	v_mul_f32_e32 v84, v66, v212
	v_mul_f32_e32 v66, v66, v213

.LBB0_128:
	s_add_i32 s37, s36, 1
	s_and_b64 s[4:5], s[80:81], exec
	s_cselect_b32 s36, s37, s36
	s_add_i32 s37, s36, 1
	s_and_b64 s[4:5], s[82:83], exec
	s_cselect_b32 s4, s37, s36
	s_xor_b32 s4, s4, s79
	s_sub_i32 s4, s4, s79
	v_lshl_or_b32 v60, s4, 6, v67
	v_ashrrev_i32_e32 v61, 31, v60
	v_mul_lo_u32 v30, s74, v61
	v_mul_lo_u32 v31, s75, v60
	v_mad_u64_u32 v[28:29], s[4:5], s74, v60, 0
	v_add3_u32 v29, v29, v30, v31
	s_ashr_i32 s79, s78, 31
	v_lshl_add_u64 v[28:29], v[28:29], 2, s[72:73]
	v_lshl_add_u64 v[28:29], s[78:79], 2, v[28:29]
	v_lshl_add_u64 v[28:29], v[28:29], 0, v[64:65]
	global_load_dwordx4 v[28:31], v[28:29], off nt
	s_cmp_lg_u64 s[76:77], 0
	s_cselect_b64 s[80:81], -1, 0
	s_cmp_eq_u64 s[76:77], 0
	v_lshl_add_u64 v[100:101], v[60:61], 2, s[76:77]
	s_cbranch_scc1 .Ltrg1_noload
	global_load_dword v206, v[100:101], off
	global_load_dword v207, v[100:101], off offset:32
	global_load_dword v208, v[100:101], off offset:64
	global_load_dword v209, v[100:101], off offset:96
	global_load_dword v210, v[100:101], off offset:128
	global_load_dword v211, v[100:101], off offset:160
	global_load_dword v212, v[100:101], off offset:192
	global_load_dword v213, v[100:101], off offset:224
.Ltrg1_noload:
	v_mov_b32_e32 v86, v80
	s_cbranch_scc1 .LBB0_130
.LBB0_130:
	v_or_b32_e32 v32, 8, v60
	v_mul_lo_u32 v61, s74, v61
	v_mul_lo_u32 v34, s75, v32
	v_mad_u64_u32 v[32:33], s[4:5], s74, v32, 0
	v_add3_u32 v33, v33, v61, v34
	v_lshl_add_u64 v[32:33], v[32:33], 2, s[72:73]
	v_lshl_add_u64 v[32:33], s[78:79], 2, v[32:33]
	v_lshl_add_u64 v[32:33], v[32:33], 0, v[64:65]
	global_load_dwordx4 v[32:35], v[32:33], off nt
	v_cndmask_b32_e64 v40, 0, 1, s[80:81]
	v_cmp_ne_u32_e64 s[4:5], 1, v40
	s_andn2_b64 vcc, exec, s[80:81]
	v_mov_b32_e32 v88, v80
	s_cbranch_vccnz .LBB0_132
.LBB0_132:
	v_or_b32_e32 v40, 16, v60
	v_mul_lo_u32 v42, s75, v40
	v_mad_u64_u32 v[40:41], s[36:37], s74, v40, 0
	v_add3_u32 v41, v41, v61, v42
	v_lshl_add_u64 v[40:41], v[40:41], 2, s[72:73]
	v_lshl_add_u64 v[40:41], s[78:79], 2, v[40:41]
	v_lshl_add_u64 v[40:41], v[40:41], 0, v[64:65]
	global_load_dwordx4 v[40:43], v[40:41], off nt
	s_and_b64 vcc, exec, s[4:5]
	v_mov_b32_e32 v90, v80
	s_cbranch_vccnz .LBB0_134
.LBB0_134:
	v_or_b32_e32 v44, 24, v60
	v_mul_lo_u32 v46, s75, v44
	v_mad_u64_u32 v[44:45], s[36:37], s74, v44, 0
	v_add3_u32 v45, v45, v61, v46
	v_lshl_add_u64 v[44:45], v[44:45], 2, s[72:73]
	v_lshl_add_u64 v[44:45], s[78:79], 2, v[44:45]
	v_lshl_add_u64 v[44:45], v[44:45], 0, v[64:65]
	global_load_dwordx4 v[44:47], v[44:45], off nt
	s_and_b64 vcc, exec, s[4:5]
	v_mov_b32_e32 v92, v80
	s_cbranch_vccnz .LBB0_136
.LBB0_136:
	v_or_b32_e32 v48, 32, v60
	v_mul_lo_u32 v50, s75, v48
	v_mad_u64_u32 v[48:49], s[36:37], s74, v48, 0
	v_add3_u32 v49, v49, v61, v50
	v_lshl_add_u64 v[48:49], v[48:49], 2, s[72:73]
	v_lshl_add_u64 v[48:49], s[78:79], 2, v[48:49]
	v_lshl_add_u64 v[48:49], v[48:49], 0, v[64:65]
	global_load_dwordx4 v[48:51], v[48:49], off nt
	s_and_b64 vcc, exec, s[4:5]
	v_mov_b32_e32 v94, v80
	s_cbranch_vccnz .LBB0_138
.LBB0_138:
	v_or_b32_e32 v52, 40, v60
	v_mul_lo_u32 v54, s75, v52
	v_mad_u64_u32 v[52:53], s[36:37], s74, v52, 0
	v_add3_u32 v53, v53, v61, v54
	v_lshl_add_u64 v[52:53], v[52:53], 2, s[72:73]
	v_lshl_add_u64 v[52:53], s[78:79], 2, v[52:53]
	v_lshl_add_u64 v[52:53], v[52:53], 0, v[64:65]
	global_load_dwordx4 v[52:55], v[52:53], off nt
	s_and_b64 vcc, exec, s[4:5]
	v_mov_b32_e32 v96, v80
	s_cbranch_vccnz .LBB0_140
.LBB0_140:
	v_or_b32_e32 v56, 48, v60
	v_mul_lo_u32 v58, s75, v56
	v_mad_u64_u32 v[56:57], s[36:37], s74, v56, 0
	v_add3_u32 v57, v57, v61, v58
	v_lshl_add_u64 v[56:57], v[56:57], 2, s[72:73]
	v_lshl_add_u64 v[56:57], s[78:79], 2, v[56:57]
	v_lshl_add_u64 v[56:57], v[56:57], 0, v[64:65]
	global_load_dwordx4 v[56:59], v[56:57], off nt
	s_and_b64 vcc, exec, s[4:5]
	v_mov_b32_e32 v98, v80
	s_cbranch_vccnz .LBB0_142
.LBB0_142:
	v_or_b32_e32 v60, 56, v60
	v_mul_lo_u32 v73, s75, v60
	v_mad_u64_u32 v[62:63], s[36:37], s74, v60, 0
	v_add3_u32 v63, v63, v61, v73
	v_lshl_add_u64 v[60:61], v[62:63], 2, s[72:73]
	v_lshl_add_u64 v[60:61], s[78:79], 2, v[60:61]
	v_lshl_add_u64 v[60:61], v[60:61], 0, v[64:65]
	global_load_dwordx4 v[60:63], v[60:61], off nt
	s_and_b64 vcc, exec, s[4:5]
	s_cbranch_vccnz .LBB0_144
.LBB0_144:
	s_and_b64 vcc, exec, s[4:5]
	s_cbranch_vccnz .Ltrg1_skip
	s_waitcnt vmcnt(7)
	v_mul_f32_e32 v86, v80, v206
	v_mul_f32_e32 v88, v80, v207
	v_mul_f32_e32 v90, v80, v208
	v_mul_f32_e32 v92, v80, v209
	v_mul_f32_e32 v94, v80, v210
	v_mul_f32_e32 v96, v80, v211
	v_mul_f32_e32 v98, v80, v212
	v_mul_f32_e32 v80, v80, v213

.LBB0_196:
	v_lshl_or_b32 v36, s36, 6, v67
	v_ashrrev_i32_e32 v37, 31, v36
	v_mul_lo_u32 v2, s76, v37
	v_mul_lo_u32 v3, s77, v36
	v_mad_u64_u32 v[0:1], s[4:5], s76, v36, 0
	v_add3_u32 v1, v1, v2, v3
	s_ashr_i32 s81, s80, 31
	v_lshl_add_u64 v[0:1], v[0:1], 2, s[74:75]
	v_lshl_add_u64 v[0:1], s[80:81], 2, v[0:1]
	v_lshl_add_u64 v[0:1], v[0:1], 0, v[64:65]
	global_load_dwordx4 v[0:3], v[0:1], off nt
	s_cmp_lg_u64 s[78:79], 0
	s_cselect_b64 s[82:83], -1, 0
	s_cmp_eq_u64 s[78:79], 0
	v_lshl_add_u64 v[100:101], v[36:37], 2, s[78:79]
	s_cbranch_scc1 .Ltrg2_noload
	global_load_dword v206, v[100:101], off
	global_load_dword v207, v[100:101], off offset:32
	global_load_dword v208, v[100:101], off offset:64
	global_load_dword v209, v[100:101], off offset:96
	global_load_dword v210, v[100:101], off offset:128
	global_load_dword v211, v[100:101], off offset:160
	global_load_dword v212, v[100:101], off offset:192
	global_load_dword v213, v[100:101], off offset:224

.LBB0_198:
	v_or_b32_e32 v4, 8, v36
	v_mul_lo_u32 v37, s76, v37
	v_mul_lo_u32 v6, s77, v4
	v_mad_u64_u32 v[4:5], s[4:5], s76, v4, 0
	v_add3_u32 v5, v5, v37, v6
	v_lshl_add_u64 v[4:5], v[4:5], 2, s[74:75]
	v_lshl_add_u64 v[4:5], s[80:81], 2, v[4:5]
	v_lshl_add_u64 v[4:5], v[4:5], 0, v[64:65]
	global_load_dwordx4 v[4:7], v[4:5], off nt
	v_cndmask_b32_e64 v8, 0, 1, s[82:83]
	v_cmp_ne_u32_e64 s[4:5], 1, v8
	s_andn2_b64 vcc, exec, s[82:83]
	v_mov_b32_e32 v70, v66
	s_cbranch_vccnz .LBB0_200
.LBB0_200:
	v_or_b32_e32 v8, 16, v36
	v_mul_lo_u32 v10, s77, v8
	v_mad_u64_u32 v[8:9], s[36:37], s76, v8, 0
	v_add3_u32 v9, v9, v37, v10
	v_lshl_add_u64 v[8:9], v[8:9], 2, s[74:75]
	v_lshl_add_u64 v[8:9], s[80:81], 2, v[8:9]
	v_lshl_add_u64 v[8:9], v[8:9], 0, v[64:65]
	global_load_dwordx4 v[8:11], v[8:9], off nt
	s_and_b64 vcc, exec, s[4:5]
	v_mov_b32_e32 v74, v66
	s_cbranch_vccnz .LBB0_202
.LBB0_202:
	v_or_b32_e32 v12, 24, v36
	v_mul_lo_u32 v14, s77, v12
	v_mad_u64_u32 v[12:13], s[36:37], s76, v12, 0
	v_add3_u32 v13, v13, v37, v14
	v_lshl_add_u64 v[12:13], v[12:13], 2, s[74:75]
	v_lshl_add_u64 v[12:13], s[80:81], 2, v[12:13]
	v_lshl_add_u64 v[12:13], v[12:13], 0, v[64:65]
	global_load_dwordx4 v[12:15], v[12:13], off nt
	s_and_b64 vcc, exec, s[4:5]
	v_mov_b32_e32 v76, v66
	s_cbranch_vccnz .LBB0_204
.LBB0_204:
	v_or_b32_e32 v16, 32, v36
	v_mul_lo_u32 v18, s77, v16
	v_mad_u64_u32 v[16:17], s[36:37], s76, v16, 0
	v_add3_u32 v17, v17, v37, v18
	v_lshl_add_u64 v[16:17], v[16:17], 2, s[74:75]
	v_lshl_add_u64 v[16:17], s[80:81], 2, v[16:17]
	v_lshl_add_u64 v[16:17], v[16:17], 0, v[64:65]
	global_load_dwordx4 v[16:19], v[16:17], off nt
	s_and_b64 vcc, exec, s[4:5]
	v_mov_b32_e32 v78, v66
	s_cbranch_vccnz .LBB0_206
.LBB0_206:
	v_or_b32_e32 v20, 40, v36
	v_mul_lo_u32 v22, s77, v20
	v_mad_u64_u32 v[20:21], s[36:37], s76, v20, 0
	v_add3_u32 v21, v21, v37, v22
	v_lshl_add_u64 v[20:21], v[20:21], 2, s[74:75]
	v_lshl_add_u64 v[20:21], s[80:81], 2, v[20:21]
	v_lshl_add_u64 v[20:21], v[20:21], 0, v[64:65]
	global_load_dwordx4 v[20:23], v[20:21], off nt
	s_and_b64 vcc, exec, s[4:5]
	v_mov_b32_e32 v82, v66
	s_cbranch_vccnz .LBB0_208
.LBB0_208:
	v_or_b32_e32 v24, 48, v36
	v_mul_lo_u32 v26, s77, v24
	v_mad_u64_u32 v[24:25], s[36:37], s76, v24, 0
	v_add3_u32 v25, v25, v37, v26
	v_lshl_add_u64 v[24:25], v[24:25], 2, s[74:75]
	v_lshl_add_u64 v[24:25], s[80:81], 2, v[24:25]
	v_lshl_add_u64 v[24:25], v[24:25], 0, v[64:65]
	global_load_dwordx4 v[24:27], v[24:25], off nt
	s_and_b64 vcc, exec, s[4:5]
	v_mov_b32_e32 v84, v66
	s_cbranch_vccnz .LBB0_210
.LBB0_210:
	v_or_b32_e32 v36, 56, v36
	v_mul_lo_u32 v73, s77, v36
	v_mad_u64_u32 v[38:39], s[36:37], s76, v36, 0
	v_add3_u32 v39, v39, v37, v73
	v_lshl_add_u64 v[36:37], v[38:39], 2, s[74:75]
	v_lshl_add_u64 v[36:37], s[80:81], 2, v[36:37]
	v_lshl_add_u64 v[36:37], v[36:37], 0, v[64:65]
	global_load_dwordx4 v[36:39], v[36:37], off nt
	s_and_b64 vcc, exec, s[4:5]
	s_cbranch_vccnz .LBB0_81
	s_and_b64 vcc, exec, s[4:5]
	s_cbranch_vccnz .LBB0_81
	s_waitcnt vmcnt(7)
	v_mul_f32_e32 v68, v66, v206
	v_mul_f32_e32 v70, v66, v207
	v_mul_f32_e32 v74, v66, v208
	v_mul_f32_e32 v76, v66, v209
	v_mul_f32_e32 v78, v66, v210
	v_mul_f32_e32 v82, v66, v211
	v_mul_f32_e32 v84, v66, v212
	v_mul_f32_e32 v66, v66, v213
	s_branch .LBB0_81
